# NA unit: Q loads issued before the K/V LDS-DMA pieces (counted waits adjusted)
# speedup vs baseline: 1.0075x; 1.0063x over previous
; __device__ __forceinline__ float bf2f(unsigned h) { return __uint_as_float(h << 16); }
; __device__ __forceinline__ void na_unit3(char* lds, const bf16_t* __restrict__ Qp, const bf16_t* __restrict__ Knp, const bf16_t* __restrict__ Vp, ...
;     ...
;   const unsigned lds0 = (unsigned)(uintptr_t)lds;
;   const int pk = (wid & 3) + 8 * (wid >> 2);
;   const int krow_n = 4 * pk + (lane >> 4);
;   const unsigned kn_off = (unsigned)(krow_n * LDK + (((lane & 15) ^ (krow_n & 15)) << 3)) * 2u;
;   const int vst_ = 2 * wid + (lane >> 5), vkk = (vst_ >> 2) * 8 + ((lane >> 2) & 7), vkey = (vkk & ~0xC) | ((vkk & 4) << 1) | ((vkk & 8) >> 1), vcol = (vst_ & 3) * 32 + (lane & 3) * 8;
;   const unsigned v_off = (unsigned)(vkey * LDK + vcol) * 2u;
;   const unsigned kn_dst = lds0 + N_KN + pk * 1024, v_dst = lds0 + N_V + wid * 1024;
;     ...
;   DMA_T(0, 0); DMA_T(1, 1); DMA_T(2, 2);
;   float l_reg = 0.f; f32x16 o[4] = {}; bf16x8 qr[8];
;   const bf16_t* Qw = Qp + (long)(wid * QBLK + r32) * LDQ + hi * 8;
; #pragma unroll
;   for (int d0 = 0; d0 < 8; ++d0) { const u32x4 raw = *reinterpret_cast<const u32x4*>(Qw + d0 * 16); u32x4 w;
; #pragma unroll
;     for (int p = 0; p < 4; ++p) w[p] = cvtpk(bf2f(raw[p] & 0xffffu) * C, bf2f(raw[p] >> 16) * C);
;     qr[d0] = *reinterpret_cast<bf16x8*>(&w); }
.LBB0_276:
	s_lshl_b32 s1, s76, 2
	s_ashr_i32 s30, s76, 9
	s_and_b32 s1, s1, 0x7c
	v_sub_u32_e64 v1, s1, 4 clamp
	s_ashr_i32 s31, s30, 31
	v_readfirstlane_b32 s85, v1
	s_lshl_b64 s[8:9], s[30:31], 13
	s_lshl_b32 s5, s1, 6
	s_or_b32 s34, s8, s5
	s_lshl_b32 s5, s85, 6
	s_or_b32 s8, s8, s5
	s_lshl_b32 s5, s76, 17
	s_lshr_b32 s0, s76, 5
	s_bfe_u32 s77, s76, 0x40005
	s_and_b32 s5, s5, 0x3800000
	s_add_u32 s5, s90, s5
	s_addc_u32 s6, s91, 0
	s_lshl_b32 s7, s76, 3
	s_and_b32 s7, s7, 0x100
	s_mov_b32 s35, s9
	s_add_u32 s81, s5, s7
	s_addc_u32 s84, s6, 0
	s_lshl_b64 s[6:7], s[34:35], 9
	s_add_u32 s6, s81, s6
	s_addc_u32 s7, s84, s7
	s_lshl_b64 s[8:9], s[8:9], 9
	s_add_u32 s5, s81, s8
	s_addc_u32 s14, s84, s9
	s_add_u32 s64, s5, 0x4000000
	s_addc_u32 s65, s14, 0
	v_mov_b32_e32 v2, v252
	s_add_u32 s78, s5, 0x8000000
	s_addc_u32 s79, s14, 0
	v_readfirstlane_b32 s10, v2
	s_ashr_i32 s15, s10, 6
	s_ashr_i32 s9, s10, 5
	s_and_b32 s8, s15, 3
	s_and_b32 s9, s9, -8
	s_or_b32 s8, s8, s9
	s_lshl_b32 s9, s8, 2
	v_bfe_u32 v1, v2, 4, 2
	v_or_b32_e32 v3, s9, v1
	v_bitop3_b32 v1, s9, v2, v1 bitop3:0x36
	s_ashr_i32 s12, s10, 4
	v_lshlrev_b32_e32 v3, 9, v3
	v_lshlrev_b32_e32 v1, 4, v1
	s_and_b32 s13, s12, 0x7ffff0
	s_lshr_b32 s12, s12, 1
	v_and_or_b32 v223, v1, s53, v3
	s_lshl_b32 s9, s15, 1
	v_lshrrev_b32_e32 v1, 2, v2
	v_lshrrev_b32_e32 v3, 1, v2
	s_and_b32 s12, s12, 4
	s_lshl_b32 s8, s8, 10
	v_bfe_u32 v222, v2, 5, 1
	v_and_or_b32 v1, v1, 3, s13
	v_and_b32_e32 v3, 8, v3
	s_cmp_lg_u32 0, -1
	v_or3_b32 v1, v1, v3, s12
	v_and_or_b32 v3, s9, 2, v222
	s_cselect_b32 s9, 0, 0
	s_add_i32 s16, s9, s8
	s_lshl_b32 s89, s15, 10
	v_lshlrev_b32_e32 v18, 4, v2
	s_add_i32 s88, s16, 0x10000
	s_add_i32 s89, s89, s9
	v_and_b32_e32 v221, 31, v2
	s_lshl_b32 s80, s15, 5
	v_or_b32_e32 v4, s80, v221
	v_ashrrev_i32_e32 v5, 31, v4
	v_lshlrev_b64 v[4:5], 9, v[4:5]
	v_lshl_add_u64 v[4:5], s[6:7], 0, v[4:5]
	v_lshlrev_b32_e32 v204, 4, v222
	v_mov_b32_e32 v205, v0
	v_lshl_add_u64 v[8:9], v[4:5], 0, v[204:205]
	global_load_dwordx4 v[160:163], v[8:9], off
	global_load_dwordx4 v[164:167], v[8:9], off offset:32
	global_load_dwordx4 v[168:171], v[8:9], off offset:64
	global_load_dwordx4 v[172:175], v[8:9], off offset:96
	global_load_dwordx4 v[176:179], v[8:9], off offset:128
	global_load_dwordx4 v[180:183], v[8:9], off offset:160
	global_load_dwordx4 v[184:187], v[8:9], off offset:192
	global_load_dwordx4 v[188:191], v[8:9], off offset:224
	s_mov_b32 m0, s88
	s_nop 0
	global_load_lds_dwordx4 v223, s[64:65]
	v_and_b32_e32 v4, 48, v18
	s_add_u32 s8, s5, 0x4002000
	v_lshl_or_b32 v3, v3, 6, v4
	s_addc_u32 s9, s14, 0
	s_add_i32 s12, s88, 0x1000
	s_mov_b32 m0, s12
	s_nop 0
	global_load_lds_dwordx4 v223, s[8:9]
	v_lshl_or_b32 v224, v1, 9, v3
	s_mov_b32 m0, s89
	s_nop 0
	global_load_lds_dwordx4 v224, s[78:79]
	s_add_u32 s8, s5, 0x8004000
	s_addc_u32 s9, s14, 0
	s_add_i32 s12, s89, 0x2000
	s_mov_b32 m0, s12
	s_nop 0
	global_load_lds_dwordx4 v224, s[8:9]
	s_add_u32 s8, s5, 0x4008000
	s_addc_u32 s9, s14, 0
	s_add_u32 s12, s5, 0x8008000
	s_addc_u32 s13, s14, 0
	s_add_i32 s17, s16, 0x14000
	s_add_i32 s18, s89, 0x4000
	s_mov_b32 m0, s17
	s_nop 0
	global_load_lds_dwordx4 v223, s[8:9]
	s_add_u32 s8, s5, 0x400a000
	s_addc_u32 s9, s14, 0
	s_add_i32 s17, s16, 0x15000
	s_mov_b32 m0, s17
	s_nop 0
	global_load_lds_dwordx4 v223, s[8:9]
	s_mov_b32 m0, s18
	s_nop 0
	global_load_lds_dwordx4 v224, s[12:13]
	s_add_u32 s8, s5, 0x800c000
	s_addc_u32 s9, s14, 0
	s_add_i32 s12, s89, 0x6000
	s_mov_b32 m0, s12
	s_nop 0
	global_load_lds_dwordx4 v224, s[8:9]
	s_add_u32 s8, s5, 0x4010000
	s_addc_u32 s9, s14, 0
	s_add_u32 s12, s5, 0x8010000
	s_addc_u32 s13, s14, 0
	s_add_i32 s17, s16, 0x18000
	s_add_i32 s18, s89, 0x8000
	s_mov_b32 m0, s17
	s_nop 0
	global_load_lds_dwordx4 v223, s[8:9]
	s_add_u32 s8, s5, 0x4012000
	s_addc_u32 s9, s14, 0
	s_add_i32 s16, s16, 0x19000
	s_mov_b32 m0, s16
	s_nop 0
	global_load_lds_dwordx4 v223, s[8:9]
	s_mov_b32 m0, s18
	s_nop 0
	global_load_lds_dwordx4 v224, s[12:13]
	s_add_u32 s8, s5, 0x8014000
	s_addc_u32 s9, s14, 0
	s_add_i32 s5, s89, 0xa000
	s_mov_b32 m0, s5
	s_nop 0
	global_load_lds_dwordx4 v224, s[8:9]
	s_movk_i32 s5, 0x1d1
	v_cmp_gt_i32_e32 vcc, s5, v2
	s_waitcnt vmcnt(19)
	v_lshlrev_b32_e32 v1, 16, v160
	v_and_b32_e32 v3, 0xffff0000, v160
	v_mul_f32_e32 v1, 0x3e0293ee, v1
	v_mul_f32_e32 v3, 0x3e0293ee, v3
	v_cvt_pk_bf16_f32 v160, v1, v3
	v_and_b32_e32 v1, 0xffff0000, v162
	v_lshlrev_b32_e32 v4, 16, v161
	v_and_b32_e32 v5, 0xffff0000, v161
	v_lshlrev_b32_e32 v10, 16, v162
	v_mul_f32_e32 v1, 0x3e0293ee, v1
	v_mul_f32_e32 v4, 0x3e0293ee, v4
	v_mul_f32_e32 v5, 0x3e0293ee, v5
	v_mul_f32_e32 v10, 0x3e0293ee, v10
	v_cvt_pk_bf16_f32 v161, v4, v5
	v_cvt_pk_bf16_f32 v162, v10, v1
	v_lshlrev_b32_e32 v1, 16, v163
	v_and_b32_e32 v3, 0xffff0000, v163
	v_mul_f32_e32 v1, 0x3e0293ee, v1
	v_mul_f32_e32 v3, 0x3e0293ee, v3
	v_cvt_pk_bf16_f32 v163, v1, v3
	s_waitcnt vmcnt(18)
	v_lshlrev_b32_e32 v1, 16, v164
	v_and_b32_e32 v3, 0xffff0000, v164
	v_lshlrev_b32_e32 v4, 16, v165
	v_and_b32_e32 v5, 0xffff0000, v165
	v_lshlrev_b32_e32 v10, 16, v166
	v_and_b32_e32 v6, 0xffff0000, v166
	v_lshlrev_b32_e32 v11, 16, v167
	v_and_b32_e32 v7, 0xffff0000, v167
	v_mul_f32_e32 v4, 0x3e0293ee, v4
	v_mul_f32_e32 v5, 0x3e0293ee, v5
	v_mul_f32_e32 v6, 0x3e0293ee, v6
	v_mul_f32_e32 v7, 0x3e0293ee, v7
	v_mul_f32_e32 v1, 0x3e0293ee, v1
	v_mul_f32_e32 v3, 0x3e0293ee, v3
	v_mul_f32_e32 v10, 0x3e0293ee, v10
	v_mul_f32_e32 v11, 0x3e0293ee, v11
	v_cvt_pk_bf16_f32 v164, v1, v3
	v_cvt_pk_bf16_f32 v165, v4, v5
	v_cvt_pk_bf16_f32 v166, v10, v6
	v_cvt_pk_bf16_f32 v167, v11, v7
	s_waitcnt vmcnt(17)
; __device__ __forceinline__ float bf2f(unsigned h) { return __uint_as_float(h << 16); }
; __device__ __forceinline__ void na_unit3(char* lds, const bf16_t* __restrict__ Qp, const bf16_t* __restrict__ Knp, const bf16_t* __restrict__ Vp, ...
;     ...
;   for (int d0 = 0; d0 < 8; ++d0) { const u32x4 raw = *reinterpret_cast<const u32x4*>(Qw + d0 * 16); u32x4 w;
; #pragma unroll
;     for (int p = 0; p < 4; ++p) w[p] = cvtpk(bf2f(raw[p] & 0xffffu) * C, bf2f(raw[p] >> 16) * C);
;     qr[d0] = *reinterpret_cast<bf16x8*>(&w); }
;   for (int i = tid; i < 15 * 31; i += NW * 64) tab[i] = rpb_h[i] * 1.4426950408889634f;
	v_lshlrev_b32_e32 v1, 16, v168
	v_and_b32_e32 v3, 0xffff0000, v168
	v_lshlrev_b32_e32 v4, 16, v169
	v_and_b32_e32 v5, 0xffff0000, v169
	v_lshlrev_b32_e32 v10, 16, v170
	v_and_b32_e32 v6, 0xffff0000, v170
	v_lshlrev_b32_e32 v11, 16, v171
	v_and_b32_e32 v7, 0xffff0000, v171
	v_mul_f32_e32 v4, 0x3e0293ee, v4
	v_mul_f32_e32 v5, 0x3e0293ee, v5
	v_mul_f32_e32 v6, 0x3e0293ee, v6
	v_mul_f32_e32 v7, 0x3e0293ee, v7
	v_mul_f32_e32 v1, 0x3e0293ee, v1
	v_mul_f32_e32 v3, 0x3e0293ee, v3
	v_mul_f32_e32 v10, 0x3e0293ee, v10
	v_mul_f32_e32 v11, 0x3e0293ee, v11
	v_cvt_pk_bf16_f32 v168, v1, v3
	v_cvt_pk_bf16_f32 v169, v4, v5
	v_cvt_pk_bf16_f32 v170, v10, v6
	v_cvt_pk_bf16_f32 v171, v11, v7
	s_waitcnt vmcnt(16)
	v_lshlrev_b32_e32 v1, 16, v172
	v_and_b32_e32 v3, 0xffff0000, v172
	v_lshlrev_b32_e32 v4, 16, v173
	v_and_b32_e32 v5, 0xffff0000, v173
	v_lshlrev_b32_e32 v10, 16, v174
	v_and_b32_e32 v6, 0xffff0000, v174
	v_lshlrev_b32_e32 v11, 16, v175
	v_and_b32_e32 v7, 0xffff0000, v175
	v_mul_f32_e32 v4, 0x3e0293ee, v4
	v_mul_f32_e32 v5, 0x3e0293ee, v5
	v_mul_f32_e32 v6, 0x3e0293ee, v6
	v_mul_f32_e32 v7, 0x3e0293ee, v7
	v_mul_f32_e32 v1, 0x3e0293ee, v1
	v_mul_f32_e32 v3, 0x3e0293ee, v3
	v_mul_f32_e32 v10, 0x3e0293ee, v10
	v_mul_f32_e32 v11, 0x3e0293ee, v11
	v_cvt_pk_bf16_f32 v172, v1, v3
	v_cvt_pk_bf16_f32 v173, v4, v5
	v_cvt_pk_bf16_f32 v174, v10, v6
	v_cvt_pk_bf16_f32 v175, v11, v7
	s_waitcnt vmcnt(15)
	v_lshlrev_b32_e32 v1, 16, v176
	v_and_b32_e32 v3, 0xffff0000, v176
	v_lshlrev_b32_e32 v4, 16, v177
	v_and_b32_e32 v5, 0xffff0000, v177
	v_lshlrev_b32_e32 v10, 16, v178
	v_and_b32_e32 v6, 0xffff0000, v178
	v_lshlrev_b32_e32 v11, 16, v179
	v_and_b32_e32 v7, 0xffff0000, v179
	v_mul_f32_e32 v4, 0x3e0293ee, v4
	v_mul_f32_e32 v5, 0x3e0293ee, v5
	v_mul_f32_e32 v6, 0x3e0293ee, v6
	v_mul_f32_e32 v7, 0x3e0293ee, v7
	v_mul_f32_e32 v1, 0x3e0293ee, v1
	v_mul_f32_e32 v3, 0x3e0293ee, v3
	v_mul_f32_e32 v10, 0x3e0293ee, v10
	v_mul_f32_e32 v11, 0x3e0293ee, v11
	v_cvt_pk_bf16_f32 v176, v1, v3
	v_cvt_pk_bf16_f32 v177, v4, v5
	v_cvt_pk_bf16_f32 v178, v10, v6
	v_cvt_pk_bf16_f32 v179, v11, v7
	s_waitcnt vmcnt(14)
	v_lshlrev_b32_e32 v1, 16, v180
	v_and_b32_e32 v3, 0xffff0000, v180
	v_lshlrev_b32_e32 v4, 16, v181
	v_and_b32_e32 v5, 0xffff0000, v181
	v_lshlrev_b32_e32 v10, 16, v182
	v_and_b32_e32 v6, 0xffff0000, v182
	v_lshlrev_b32_e32 v11, 16, v183
	v_and_b32_e32 v7, 0xffff0000, v183
	v_mul_f32_e32 v4, 0x3e0293ee, v4
	v_mul_f32_e32 v5, 0x3e0293ee, v5
	v_mul_f32_e32 v6, 0x3e0293ee, v6
	v_mul_f32_e32 v7, 0x3e0293ee, v7
	v_mul_f32_e32 v1, 0x3e0293ee, v1
	v_mul_f32_e32 v3, 0x3e0293ee, v3
	v_mul_f32_e32 v10, 0x3e0293ee, v10
	v_mul_f32_e32 v11, 0x3e0293ee, v11
	v_cvt_pk_bf16_f32 v180, v1, v3
	v_cvt_pk_bf16_f32 v181, v4, v5
	v_cvt_pk_bf16_f32 v182, v10, v6
	v_cvt_pk_bf16_f32 v183, v11, v7
	s_waitcnt vmcnt(13)
	v_lshlrev_b32_e32 v1, 16, v184
	v_and_b32_e32 v3, 0xffff0000, v184
	v_lshlrev_b32_e32 v4, 16, v185
	v_and_b32_e32 v5, 0xffff0000, v185
	v_lshlrev_b32_e32 v10, 16, v186
	v_and_b32_e32 v6, 0xffff0000, v186
	v_lshlrev_b32_e32 v11, 16, v187
	v_and_b32_e32 v7, 0xffff0000, v187
	v_mul_f32_e32 v4, 0x3e0293ee, v4
	v_mul_f32_e32 v5, 0x3e0293ee, v5
	v_mul_f32_e32 v6, 0x3e0293ee, v6
	v_mul_f32_e32 v7, 0x3e0293ee, v7
	v_mul_f32_e32 v1, 0x3e0293ee, v1
	v_mul_f32_e32 v3, 0x3e0293ee, v3
	v_mul_f32_e32 v10, 0x3e0293ee, v10
	v_mul_f32_e32 v11, 0x3e0293ee, v11
	v_cvt_pk_bf16_f32 v184, v1, v3
	v_cvt_pk_bf16_f32 v185, v4, v5
	v_cvt_pk_bf16_f32 v186, v10, v6
	v_cvt_pk_bf16_f32 v187, v11, v7
	s_waitcnt vmcnt(12)
	v_lshlrev_b32_e32 v1, 16, v188
	v_and_b32_e32 v3, 0xffff0000, v188
	v_lshlrev_b32_e32 v4, 16, v189
	v_and_b32_e32 v5, 0xffff0000, v189
	v_lshlrev_b32_e32 v8, 16, v190
	v_and_b32_e32 v6, 0xffff0000, v190
	v_lshlrev_b32_e32 v9, 16, v191
	v_and_b32_e32 v7, 0xffff0000, v191
	v_mul_f32_e32 v1, 0x3e0293ee, v1
	v_mul_f32_e32 v3, 0x3e0293ee, v3
	v_mul_f32_e32 v4, 0x3e0293ee, v4
	v_mul_f32_e32 v5, 0x3e0293ee, v5
	v_mul_f32_e32 v8, 0x3e0293ee, v8
	v_mul_f32_e32 v6, 0x3e0293ee, v6
	v_mul_f32_e32 v9, 0x3e0293ee, v9
	v_mul_f32_e32 v7, 0x3e0293ee, v7
	v_cvt_pk_bf16_f32 v188, v1, v3
	v_cvt_pk_bf16_f32 v189, v4, v5
	v_cvt_pk_bf16_f32 v190, v8, v6
	v_cvt_pk_bf16_f32 v191, v9, v7
	s_and_saveexec_b64 s[6:7], vcc
	s_cbranch_execz .LBB0_284
	v_max_i32_e32 v1, 0xffffffd1, v2
	v_sub_u32_e32 v1, v1, v2
	v_add_u32_e32 v1, 0x1ff, v1
	s_movk_i32 s5, 0x1ff
	v_cmp_lt_u32_e32 vcc, s5, v1
	s_mov_b64 s[26:27], -1
	v_mov_b32_e32 v4, v2
	s_and_saveexec_b64 s[8:9], vcc
	s_cbranch_execz .LBB0_281
	v_lshrrev_b32_e32 v1, 9, v1
	s_or_b32 s5, s77, s20
	v_readlane_b32 s12, v255, 0
	v_add_u32_e32 v1, 1, v1
	s_mulk_i32 s5, 0x744
	v_readlane_b32 s14, v255, 2
	v_readlane_b32 s15, v255, 3
	s_add_u32 s26, s14, s5
	v_and_b32_e32 v6, 0xfffffe, v1
	v_add_u32_e32 v3, 0x200, v2
	v_readlane_b32 s5, v254, 27
	s_addc_u32 s27, s15, 0
	s_mov_b64 s[36:37], 0
	v_lshl_add_u32 v7, v2, 2, s5
	v_mov_b32_e32 v8, v6
	v_mov_b64_e32 v[4:5], v[2:3]
	v_readlane_b32 s13, v255, 1
	v_readlane_b32 s16, v255, 4
	v_readlane_b32 s17, v255, 5
	v_readlane_b32 s18, v255, 6
	v_readlane_b32 s19, v255, 7
